# SEAM4 counter: arrive first, guard words and first poll fetched in the same round trip
# speedup vs baseline: 1.0026x; 1.0026x over previous
.LBB0_511:
	s_cmp_gt_i32 s91, 5
	s_cselect_b64 s[4:5], -1, 0
	s_and_b64 s[0:1], s[0:1], s[4:5]
	s_andn2_b64 vcc, exec, s[0:1]
	s_cbranch_vccnz .LBB0_565
	s_waitcnt vmcnt(0)
	s_waitcnt vmcnt(0) lgkmcnt(0)
	s_barrier
	s_and_saveexec_b64 s[0:1], s[84:85]
	s_cbranch_execz .LBB0_564
	s_and_b32 s98, s2, 7
	s_lshl_b32 s98, s98, 3
	s_bfe_u32 s99, s2, 0x30003
	s_add_i32 s98, s98, s99
	s_lshl_b32 s98, s98, 6
	s_add_i32 s98, s98, 0xd000
	v_mov_b32_e32 v2, s98
	v_mov_b32_e32 v3, 1
	global_atomic_add v2, v3, s[88:89]
	v_mov_b32_e32 v0, 0xe000
	global_load_dwordx4 v[4:7], v0, s[88:89] sc1
	global_load_dwordx4 v[8:11], v0, s[88:89] offset:16 sc1
	global_load_dwordx4 v[12:15], v0, s[88:89] offset:32 sc1
	global_load_dwordx4 v[16:19], v0, s[88:89] offset:48 sc1
	global_load_dword v1, v2, s[88:89] sc1
	s_waitcnt vmcnt(0)
	v_add_u32_e32 v4, v4, v5
	v_add_u32_e32 v6, v6, v7
	v_add_u32_e32 v8, v8, v9
	v_add_u32_e32 v10, v10, v11
	v_add_u32_e32 v12, v12, v13
	v_add_u32_e32 v14, v14, v15
	v_add_u32_e32 v16, v16, v17
	v_add_u32_e32 v18, v18, v19
	v_xor_b32_e32 v4, 17, v4
	v_xor_b32_e32 v6, 17, v6
	v_xor_b32_e32 v8, 17, v8
	v_xor_b32_e32 v10, 17, v10
	v_xor_b32_e32 v12, 17, v12
	v_xor_b32_e32 v14, 17, v14
	v_xor_b32_e32 v16, 17, v16
	v_xor_b32_e32 v18, 17, v18
	v_or3_b32 v4, v4, v6, v8
	v_or3_b32 v10, v10, v12, v14
	v_or3_b32 v4, v4, v16, v18
	v_or_b32_e32 v4, v4, v10
	v_cmp_ne_u32_e32 vcc, 0, v4
	s_cbranch_vccnz .Lg4_orig
.Lg4_chk:
	v_cmp_gt_u32_e32 vcc, 4, v1
	s_cbranch_vccz .LBB0_564
	s_sleep 1
	global_load_dword v1, v2, s[88:89] sc1
	s_waitcnt vmcnt(0)
	s_branch .Lg4_chk
